# grid barrier thread-0 part hand-written: scalar control flow, 2 staggered polls in flight, f32 reciprocal instead of integer division
# speedup vs baseline: 1.0386x; 1.0033x over previous
.LBB0_111:
	s_lshl_b32 s2, s59, 8
	s_addk_i32 s2, 0x1400
	v_mov_b32_e32 v4, 1
	v_mov_b32_e32 v2, s2
	s_nop 3
	global_atomic_add v5, v2, v4, s[60:61] sc0
	buffer_inv sc1
	s_waitcnt lgkmcnt(0)
	v_cvt_f32_u32_e32 v6, v3
	v_readfirstlane_b32 s8, v3
	v_readfirstlane_b32 s9, v1
	v_rcp_f32_e32 v6, v6
	v_mov_b32_e32 v2, 0x3400
	s_waitcnt vmcnt(1)
	v_readfirstlane_b32 s2, v5
	v_cvt_f32_u32_e32 v5, v5
	s_nop 0
	v_add_f32_e32 v5, 0.5, v5
	v_mul_f32_e32 v5, v5, v6
	v_cvt_u32_f32_e32 v5, v5
	s_nop 0
	v_readfirstlane_b32 s3, v5
	s_nop 3
	s_add_i32 s3, s3, 1
	s_add_i32 s2, s2, 1
	s_mul_i32 s8, s3, s8
	s_mul_i32 s9, s3, s9
	s_cmp_lg_u32 s2, s8
	s_cbranch_scc1 .Lsm0_poll
	buffer_wbl2 sc1
	s_waitcnt vmcnt(0)
	global_atomic_add v5, v2, v4, s[60:61] sc0
	s_waitcnt vmcnt(0)
	v_readfirstlane_b32 s2, v5
	s_nop 3
	s_add_i32 s2, s2, 1
	s_cmp_eq_u32 s2, s9
	s_cbranch_scc1 .Lsm0_done
.Lsm0_poll:
	s_mov_b32 s10, 0
.Lsm0_prime:
	global_load_dword v252, v2, s[60:61] sc1
	s_sleep 14
	global_load_dword v253, v2, s[60:61] sc1
.Lsm0_loop:
	s_waitcnt vmcnt(1)
	v_readfirstlane_b32 s2, v252
	s_nop 3
	s_cmp_ge_u32 s2, s9
	s_cbranch_scc1 .Lsm0_done
	global_load_dword v252, v2, s[60:61] sc1
	s_waitcnt vmcnt(1)
	v_readfirstlane_b32 s2, v253
	s_nop 3
	s_cmp_ge_u32 s2, s9
	s_cbranch_scc1 .Lsm0_done
	global_load_dword v253, v2, s[60:61] sc1
	s_add_i32 s10, s10, 1
	s_and_b32 s2, s10, 127
	s_cmp_lg_u32 s2, 0
	s_cbranch_scc1 .Lsm0_loop
	v_mov_b32_e32 v6, 0x200
	global_load_dword v255, v6, s[60:61] sc1
	s_waitcnt vmcnt(0)
	v_readfirstlane_b32 s2, v255
	s_nop 3
	s_cmp_lg_u32 s2, 0
	s_cbranch_scc1 .Lsm0_done
	s_cmp_lt_u32 s10, 0x20000
	s_cbranch_scc1 .Lsm0_prime
	global_atomic_add v6, v4, s[60:61]
	s_waitcnt vmcnt(0)
.Lsm0_done:
.LBB0_147:
	s_or_b64 exec, exec, s[6:7]
	s_waitcnt lgkmcnt(0)
	s_barrier

.LBB0_328:
	s_lshl_b32 s2, s59, 8
	s_addk_i32 s2, 0x1400
	v_mov_b32_e32 v4, 1
	v_mov_b32_e32 v2, s2
	s_nop 3
	global_atomic_add v5, v2, v4, s[60:61] sc0
	buffer_inv sc1
	s_waitcnt lgkmcnt(0)
	v_cvt_f32_u32_e32 v6, v3
	v_readfirstlane_b32 s6, v3
	v_readfirstlane_b32 s7, v1
	v_rcp_f32_e32 v6, v6
	v_mov_b32_e32 v2, 0x3400
	s_waitcnt vmcnt(1)
	v_readfirstlane_b32 s2, v5
	v_cvt_f32_u32_e32 v5, v5
	s_nop 0
	v_add_f32_e32 v5, 0.5, v5
	v_mul_f32_e32 v5, v5, v6
	v_cvt_u32_f32_e32 v5, v5
	s_nop 0
	v_readfirstlane_b32 s3, v5
	s_nop 3
	s_add_i32 s3, s3, 1
	s_add_i32 s2, s2, 1
	s_mul_i32 s6, s3, s6
	s_mul_i32 s7, s3, s7
	s_cmp_lg_u32 s2, s6
	s_cbranch_scc1 .Lsm1_poll
	buffer_wbl2 sc1
	s_waitcnt vmcnt(0)
	global_atomic_add v5, v2, v4, s[60:61] sc0
	s_waitcnt vmcnt(0)
	v_readfirstlane_b32 s2, v5
	s_nop 3
	s_add_i32 s2, s2, 1
	s_cmp_eq_u32 s2, s7
	s_cbranch_scc1 .Lsm1_done
.Lsm1_poll:
	s_mov_b32 s8, 0

.Lsm1_loop:
	s_waitcnt vmcnt(1)
	v_readfirstlane_b32 s2, v252
	s_nop 3
	s_cmp_ge_u32 s2, s7
	s_cbranch_scc1 .Lsm1_done
	global_load_dword v252, v2, s[60:61] sc1
	s_waitcnt vmcnt(1)
	v_readfirstlane_b32 s2, v253
	s_nop 3
	s_cmp_ge_u32 s2, s7
	s_cbranch_scc1 .Lsm1_done
	global_load_dword v253, v2, s[60:61] sc1
	s_add_i32 s8, s8, 1
	s_and_b32 s2, s8, 127
	s_cmp_lg_u32 s2, 0
	s_cbranch_scc1 .Lsm1_loop
	v_mov_b32_e32 v6, 0x200
	global_load_dword v255, v6, s[60:61] sc1
	s_waitcnt vmcnt(0)
	v_readfirstlane_b32 s2, v255
	s_nop 3
	s_cmp_lg_u32 s2, 0
	s_cbranch_scc1 .Lsm1_done
	s_cmp_lt_u32 s8, 0x20000
	s_cbranch_scc1 .Lsm1_prime
	global_atomic_add v6, v4, s[60:61]
	s_waitcnt vmcnt(0)
.Lsm1_done:
.LBB0_364:
	s_or_b64 exec, exec, s[4:5]
	s_waitcnt lgkmcnt(0)
	s_barrier

.LBB0_598:
	s_lshl_b32 s2, s59, 8
	s_addk_i32 s2, 0x1400
	v_mov_b32_e32 v5, 1
	v_mov_b32_e32 v3, s2
	s_nop 3
	global_atomic_add v6, v3, v5, s[60:61] sc0
	buffer_inv sc1
	s_waitcnt lgkmcnt(0)
	v_cvt_f32_u32_e32 v7, v4
	v_readfirstlane_b32 s6, v4
	v_readfirstlane_b32 s7, v2
	v_rcp_f32_e32 v7, v7
	v_mov_b32_e32 v3, 0x3400
	s_waitcnt vmcnt(1)
	v_readfirstlane_b32 s2, v6
	v_cvt_f32_u32_e32 v6, v6
	s_nop 0
	v_add_f32_e32 v6, 0.5, v6
	v_mul_f32_e32 v6, v6, v7
	v_cvt_u32_f32_e32 v6, v6
	s_nop 0
	v_readfirstlane_b32 s3, v6
	s_nop 3
	s_add_i32 s3, s3, 1
	s_add_i32 s2, s2, 1
	s_mul_i32 s6, s3, s6
	s_mul_i32 s7, s3, s7
	s_cmp_lg_u32 s2, s6
	s_cbranch_scc1 .Lsm3_poll
	buffer_wbl2 sc1
	s_waitcnt vmcnt(0)
	global_atomic_add v6, v3, v5, s[60:61] sc0
	s_waitcnt vmcnt(0)
	v_readfirstlane_b32 s2, v6
	s_nop 3
	s_add_i32 s2, s2, 1
	s_cmp_eq_u32 s2, s7
	s_cbranch_scc1 .Lsm3_done

.Lsm3_prime:
	global_load_dword v252, v3, s[60:61] sc1
	s_sleep 14
	global_load_dword v253, v3, s[60:61] sc1
.Lsm3_loop:
	s_waitcnt vmcnt(1)
	v_readfirstlane_b32 s2, v252
	s_nop 3
	s_cmp_ge_u32 s2, s7
	s_cbranch_scc1 .Lsm3_done
	global_load_dword v252, v3, s[60:61] sc1
	s_waitcnt vmcnt(1)
	v_readfirstlane_b32 s2, v253
	s_nop 3
	s_cmp_ge_u32 s2, s7
	s_cbranch_scc1 .Lsm3_done
	global_load_dword v253, v3, s[60:61] sc1
	s_add_i32 s8, s8, 1
	s_and_b32 s2, s8, 127
	s_cmp_lg_u32 s2, 0
	s_cbranch_scc1 .Lsm3_loop
	v_mov_b32_e32 v7, 0x200
	global_load_dword v255, v7, s[60:61] sc1
	s_waitcnt vmcnt(0)
	v_readfirstlane_b32 s2, v255
	s_nop 3
	s_cmp_lg_u32 s2, 0
	s_cbranch_scc1 .Lsm3_done
	s_cmp_lt_u32 s8, 0x20000
	s_cbranch_scc1 .Lsm3_prime
	global_atomic_add v7, v5, s[60:61]
	s_waitcnt vmcnt(0)

.LBB0_658:
	s_lshl_b32 s2, s59, 8
	s_addk_i32 s2, 0x1400
	v_mov_b32_e32 v5, 1
	v_mov_b32_e32 v3, s2
	s_nop 3
	global_atomic_add v6, v3, v5, s[60:61] sc0
	buffer_inv sc1
	s_waitcnt lgkmcnt(0)
	v_cvt_f32_u32_e32 v7, v4
	v_readfirstlane_b32 s4, v4
	v_readfirstlane_b32 s5, v2
	v_rcp_f32_e32 v7, v7
	v_mov_b32_e32 v3, 0x3400
	s_waitcnt vmcnt(1)
	v_readfirstlane_b32 s2, v6
	v_cvt_f32_u32_e32 v6, v6
	s_nop 0
	v_add_f32_e32 v6, 0.5, v6
	v_mul_f32_e32 v6, v6, v7
	v_cvt_u32_f32_e32 v6, v6
	s_nop 0
	v_readfirstlane_b32 s3, v6
	s_nop 3
	s_add_i32 s3, s3, 1
	s_add_i32 s2, s2, 1
	s_mul_i32 s4, s3, s4
	s_mul_i32 s5, s3, s5
	s_cmp_lg_u32 s2, s4
	s_cbranch_scc1 .Lsm4_poll
	buffer_wbl2 sc1
	s_waitcnt vmcnt(0)
	global_atomic_add v6, v3, v5, s[60:61] sc0
	s_waitcnt vmcnt(0)
	v_readfirstlane_b32 s2, v6
	s_nop 3
	s_add_i32 s2, s2, 1
	s_cmp_eq_u32 s2, s5
	s_cbranch_scc1 .Lsm4_done
.Lsm4_poll:
	s_mov_b32 s6, 0

.Lsm4_loop:
	s_waitcnt vmcnt(1)
	v_readfirstlane_b32 s2, v252
	s_nop 3
	s_cmp_ge_u32 s2, s5
	s_cbranch_scc1 .Lsm4_done
	global_load_dword v252, v3, s[60:61] sc1
	s_waitcnt vmcnt(1)
	v_readfirstlane_b32 s2, v253
	s_nop 3
	s_cmp_ge_u32 s2, s5
	s_cbranch_scc1 .Lsm4_done
	global_load_dword v253, v3, s[60:61] sc1
	s_add_i32 s6, s6, 1
	s_and_b32 s2, s6, 127
	s_cmp_lg_u32 s2, 0
	s_cbranch_scc1 .Lsm4_loop
	v_mov_b32_e32 v7, 0x200
	global_load_dword v255, v7, s[60:61] sc1
	s_waitcnt vmcnt(0)
	v_readfirstlane_b32 s2, v255
	s_nop 3
	s_cmp_lg_u32 s2, 0
	s_cbranch_scc1 .Lsm4_done
	s_cmp_lt_u32 s6, 0x20000
	s_cbranch_scc1 .Lsm4_prime
	global_atomic_add v7, v5, s[60:61]
	s_waitcnt vmcnt(0)
.Lsm4_done:
.LBB0_694:
	s_or_b64 exec, exec, s[0:1]
	s_waitcnt lgkmcnt(0)
	s_barrier

.LBB0_740:
	s_lshl_b32 s2, s59, 8
	s_addk_i32 s2, 0x1400
	v_mov_b32_e32 v5, 1
	v_mov_b32_e32 v3, s2
	s_nop 3
	global_atomic_add v6, v3, v5, s[60:61] sc0
	buffer_inv sc1
	s_waitcnt lgkmcnt(0)
	v_cvt_f32_u32_e32 v7, v4
	v_readfirstlane_b32 s8, v4
	v_readfirstlane_b32 s9, v2
	v_rcp_f32_e32 v7, v7
	v_mov_b32_e32 v3, 0x3400
	s_waitcnt vmcnt(1)
	v_readfirstlane_b32 s2, v6
	v_cvt_f32_u32_e32 v6, v6
	s_nop 0
	v_add_f32_e32 v6, 0.5, v6
	v_mul_f32_e32 v6, v6, v7
	v_cvt_u32_f32_e32 v6, v6
	s_nop 0
	v_readfirstlane_b32 s3, v6
	s_nop 3
	s_add_i32 s3, s3, 1
	s_add_i32 s2, s2, 1
	s_mul_i32 s8, s3, s8
	s_mul_i32 s9, s3, s9
	s_cmp_lg_u32 s2, s8
	s_cbranch_scc1 .Lsm5_poll
	buffer_wbl2 sc1
	s_waitcnt vmcnt(0)
	global_atomic_add v6, v3, v5, s[60:61] sc0
	s_waitcnt vmcnt(0)
	v_readfirstlane_b32 s2, v6
	s_nop 3
	s_add_i32 s2, s2, 1
	s_cmp_eq_u32 s2, s9
	s_cbranch_scc1 .Lsm5_done

.Lsm5_loop:
	s_waitcnt vmcnt(1)
	v_readfirstlane_b32 s2, v252
	s_nop 3
	s_cmp_ge_u32 s2, s9
	s_cbranch_scc1 .Lsm5_done
	global_load_dword v252, v3, s[60:61] sc1
	s_waitcnt vmcnt(1)
	v_readfirstlane_b32 s2, v253
	s_nop 3
	s_cmp_ge_u32 s2, s9
	s_cbranch_scc1 .Lsm5_done
	global_load_dword v253, v3, s[60:61] sc1
	s_add_i32 s10, s10, 1
	s_and_b32 s2, s10, 127
	s_cmp_lg_u32 s2, 0
	s_cbranch_scc1 .Lsm5_loop
	v_mov_b32_e32 v7, 0x200
	global_load_dword v255, v7, s[60:61] sc1
	s_waitcnt vmcnt(0)
	v_readfirstlane_b32 s2, v255
	s_nop 3
	s_cmp_lg_u32 s2, 0
	s_cbranch_scc1 .Lsm5_done
	s_cmp_lt_u32 s10, 0x20000
	s_cbranch_scc1 .Lsm5_prime
	global_atomic_add v7, v5, s[60:61]
	s_waitcnt vmcnt(0)
